# final normalisation reads each row on the XCD whose L2 last wrote it (writer-XCD affinity, last round first)
# speedup vs baseline: 1.0045x; 1.0045x over previous
; __device__ __forceinline__ void final_phase(const Params& p) {
;   const float* part = (const float*)(p.ws + O_PART);
;   const float* g = p.in[40];
;   const int lane = threadIdx.x & 63, wave = threadIdx.x >> 6;
;   for (int row = blockIdx.x * 8 + wave; row < MT; row += gridDim.x * 8) {
;     float s = (lane < 16) ? part[(size_t)row * 16 + lane] : 0.f;
;     s = wsum64(s);
;     const float rs = rsqrtf(s * (1.0f / 1024.0f) + 1e-6f);
;     float* xr = p.out + (size_t)row * 1024;
; #pragma unroll
;     for (int i = 0; i < 4; i++) {
;       float4 v = *(float4*)(xr + i * 256 + lane * 4);
;       float4 gg = *(const float4*)(g + i * 256 + lane * 4);
;       v.x *= rs * gg.x; v.y *= rs * gg.y; v.z *= rs * gg.z; v.w *= rs * gg.w;
;       *(float4*)(xr + i * 256 + lane * 4) = v;
;     }
;   }
.LBB0_2340:
	v_lshrrev_b32_e32 v42, 6, v128
	v_and_b32_e32 v43, 63, v128
	v_readlane_b32 s1, v254, 0
	v_readfirstlane_b32 s0, v42
	v_lshlrev_b32_e32 v40, 4, v43
	v_and_b32_e32 v44, 15, v43
	v_lshlrev_b32_e32 v41, 2, v44
	v_cmp_gt_u32_e32 vcc, 16, v43
	s_and_b32 s16, s1, 7
	s_lshl_b32 s16, s16, 10
	s_lshr_b32 s17, s1, 3
	s_lshl_b32 s17, s17, 5
	s_add_u32 s16, s16, s17
	s_add_u32 s16, s16, s0
	s_add_u32 s2, s16, 8192
	s_lshl_b32 s17, s1, 3
	s_add_u32 s17, s17, s0
	s_add_u32 s17, s17, 16384
	s_cmp_lt_u32 s1, 64
	s_cselect_b32 s18, 9, 8
	s_mov_b32 s3, 0
	s_lshl_b32 s12, s42, 3
	s_add_u32 s96, s96, 0x2e00100
	s_addc_u32 s97, s97, 0
	global_load_dwordx4 v[16:19], v40, s[92:93]
	global_load_dwordx4 v[20:23], v40, s[92:93] offset:1024
	global_load_dwordx4 v[24:27], v40, s[92:93] offset:2048
	global_load_dwordx4 v[28:31], v40, s[92:93] offset:3072
	s_mov_b32 s14, s2
	s_lshl_b32 s4, s2, 12
	s_add_u32 s8, s94, s4
	s_addc_u32 s9, s95, 0
	s_lshl_b32 s4, s2, 6
	s_add_u32 s6, s96, s4
	s_addc_u32 s7, s97, 0
	global_load_dwordx4 v[0:3], v40, s[8:9]
	global_load_dwordx4 v[4:7], v40, s[8:9] offset:1024
	global_load_dwordx4 v[8:11], v40, s[8:9] offset:2048
	global_load_dwordx4 v[12:15], v40, s[8:9] offset:3072
	global_load_dword v32, v41, s[6:7]
	s_add_u32 s3, s3, 1
	s_add_u32 s2, s2, 8
	s_cmp_eq_u32 s3, 4
	s_cselect_b32 s2, s16, s2
	s_cmp_eq_u32 s3, 8
	s_cselect_b32 s2, s17, s2
	s_cmp_ge_u32 s3, s18
	s_mov_b32 s15, s2
	s_lshl_b32 s4, s2, 12
	s_add_u32 s10, s94, s4
	s_addc_u32 s11, s95, 0
	s_lshl_b32 s4, s2, 6
	s_add_u32 s6, s96, s4
	s_addc_u32 s7, s97, 0
	global_load_dwordx4 v[48:51], v40, s[10:11]
	global_load_dwordx4 v[52:55], v40, s[10:11] offset:1024
	global_load_dwordx4 v[56:59], v40, s[10:11] offset:2048
	global_load_dwordx4 v[60:63], v40, s[10:11] offset:3072
	global_load_dword v80, v41, s[6:7]
	s_waitcnt vmcnt(5)
	s_cmp_lt_u32 s14, 16384
	s_cbranch_scc1 .Lfin_prompt_f
	v_mul_f32_e32 v42, v0, v0
	v_fmac_f32_e32 v42, v1, v1
	v_fmac_f32_e32 v42, v2, v2
	v_fmac_f32_e32 v42, v3, v3
	v_fmac_f32_e32 v42, v4, v4
	v_fmac_f32_e32 v42, v5, v5
	v_fmac_f32_e32 v42, v6, v6
	v_fmac_f32_e32 v42, v7, v7
	v_fmac_f32_e32 v42, v8, v8
	v_fmac_f32_e32 v42, v9, v9
	v_fmac_f32_e32 v42, v10, v10
	v_fmac_f32_e32 v42, v11, v11
	v_fmac_f32_e32 v42, v12, v12
	v_fmac_f32_e32 v42, v13, v13
	v_fmac_f32_e32 v42, v14, v14
	v_fmac_f32_e32 v42, v15, v15
	s_branch .Lfin_sum_f

; __device__ __forceinline__ void final_phase(const Params& p) {
;     ...
;   for (int row = blockIdx.x * 8 + wave; row < MT; row += gridDim.x * 8) {
;     float s = (lane < 16) ? part[(size_t)row * 16 + lane] : 0.f;
;     s = wsum64(s);
;     const float rs = rsqrtf(s * (1.0f / 1024.0f) + 1e-6f);
;     float* xr = p.out + (size_t)row * 1024;
; #pragma unroll
;     for (int i = 0; i < 4; i++) {
;       float4 v = *(float4*)(xr + i * 256 + lane * 4);
;       float4 gg = *(const float4*)(g + i * 256 + lane * 4);
;       v.x *= rs * gg.x; v.y *= rs * gg.y; v.z *= rs * gg.z; v.w *= rs * gg.w;
;       *(float4*)(xr + i * 256 + lane * 4) = v;
;     }
;   }
.Lfin_loop:
	s_mov_b32 s13, 0
	s_add_u32 s3, s3, 1
	s_add_u32 s2, s2, 8
	s_cmp_eq_u32 s3, 4
	s_cselect_b32 s2, s16, s2
	s_cmp_eq_u32 s3, 8
	s_cselect_b32 s2, s17, s2
	s_cmp_ge_u32 s3, s18
	s_cbranch_scc1 .Lfin_nomore_a
	s_mov_b32 s14, s2
	s_lshl_b32 s4, s2, 12
	s_add_u32 s8, s94, s4
	s_addc_u32 s9, s95, 0
	s_lshl_b32 s4, s2, 6
	s_add_u32 s6, s96, s4
	s_addc_u32 s7, s97, 0
	global_load_dwordx4 v[0:3], v40, s[8:9]
	global_load_dwordx4 v[4:7], v40, s[8:9] offset:1024
	global_load_dwordx4 v[8:11], v40, s[8:9] offset:2048
	global_load_dwordx4 v[12:15], v40, s[8:9] offset:3072
	global_load_dword v32, v41, s[6:7]
	s_waitcnt vmcnt(9)
	s_branch .Lfin_go_a

; __device__ __forceinline__ void final_phase(const Params& p) {
;     ...
;   for (int row = blockIdx.x * 8 + wave; row < MT; row += gridDim.x * 8) {
;     float s = (lane < 16) ? part[(size_t)row * 16 + lane] : 0.f;
;     s = wsum64(s);
;     const float rs = rsqrtf(s * (1.0f / 1024.0f) + 1e-6f);
;     float* xr = p.out + (size_t)row * 1024;
; #pragma unroll
;     for (int i = 0; i < 4; i++) {
;       float4 v = *(float4*)(xr + i * 256 + lane * 4);
;       float4 gg = *(const float4*)(g + i * 256 + lane * 4);
;       v.x *= rs * gg.x; v.y *= rs * gg.y; v.z *= rs * gg.z; v.w *= rs * gg.w;
;       *(float4*)(xr + i * 256 + lane * 4) = v;
;     }
;   }
.Lfin_sum_a:
	s_nop 1
	v_add_f32_dpp v42, v42, v42 quad_perm:[1,0,3,2] row_mask:0xf bank_mask:0xf
	s_nop 1
	v_add_f32_dpp v42, v42, v42 quad_perm:[2,3,0,1] row_mask:0xf bank_mask:0xf
	s_nop 1
	v_add_f32_dpp v42, v42, v42 row_half_mirror row_mask:0xf bank_mask:0xf
	s_nop 1
	v_add_f32_dpp v42, v42, v42 row_mirror row_mask:0xf bank_mask:0xf
	v_mov_b32_e32 v43, v42
	s_nop 1
	v_permlane16_swap_b32_e32 v43, v42
	v_add_f32_e32 v42, v42, v43
	v_mov_b32_e32 v43, v42
	s_nop 1
	v_permlane32_swap_b32_e32 v43, v42
	v_add_f32_e32 v42, v42, v43
	v_mov_b32_e32 v43, 0x358637bd
	v_fmamk_f32 v42, v42, 0x3a800000, v43
	v_rsq_f32_e32 v42, v42
	s_nop 0
	v_mul_f32_e32 v44, v42, v16
	v_mul_f32_e32 v48, v48, v44
	v_mul_f32_e32 v45, v42, v17
	v_mul_f32_e32 v49, v49, v45
	v_mul_f32_e32 v46, v42, v18
	v_mul_f32_e32 v50, v50, v46
	v_mul_f32_e32 v47, v42, v19
	v_mul_f32_e32 v51, v51, v47
	v_mul_f32_e32 v44, v42, v20
	v_mul_f32_e32 v52, v52, v44
	v_mul_f32_e32 v45, v42, v21
	v_mul_f32_e32 v53, v53, v45
	v_mul_f32_e32 v46, v42, v22
	v_mul_f32_e32 v54, v54, v46
	v_mul_f32_e32 v47, v42, v23
	v_mul_f32_e32 v55, v55, v47
	v_mul_f32_e32 v44, v42, v24
	v_mul_f32_e32 v56, v56, v44
	v_mul_f32_e32 v45, v42, v25
	v_mul_f32_e32 v57, v57, v45
	v_mul_f32_e32 v46, v42, v26
	v_mul_f32_e32 v58, v58, v46
	v_mul_f32_e32 v47, v42, v27
	v_mul_f32_e32 v59, v59, v47
	v_mul_f32_e32 v44, v42, v28
	v_mul_f32_e32 v60, v60, v44
	v_mul_f32_e32 v45, v42, v29
	v_mul_f32_e32 v61, v61, v45
	v_mul_f32_e32 v46, v42, v30
	v_mul_f32_e32 v62, v62, v46
	v_mul_f32_e32 v47, v42, v31
	v_mul_f32_e32 v63, v63, v47
	global_store_dwordx4 v40, v[48:51], s[10:11]
	global_store_dwordx4 v40, v[52:55], s[10:11] offset:1024
	global_store_dwordx4 v40, v[56:59], s[10:11] offset:2048
	global_store_dwordx4 v40, v[60:63], s[10:11] offset:3072
	s_cmp_eq_u32 s13, 1
	s_cbranch_scc1 .Lfin_done
	s_mov_b32 s13, 0
	s_add_u32 s3, s3, 1
	s_add_u32 s2, s2, 8
	s_cmp_eq_u32 s3, 4
	s_cselect_b32 s2, s16, s2
	s_cmp_eq_u32 s3, 8
	s_cselect_b32 s2, s17, s2
	s_cmp_ge_u32 s3, s18
	s_cbranch_scc1 .Lfin_nomore_b
	s_mov_b32 s15, s2
	s_lshl_b32 s4, s2, 12
	s_add_u32 s10, s94, s4
	s_addc_u32 s11, s95, 0
	s_lshl_b32 s4, s2, 6
	s_add_u32 s6, s96, s4
	s_addc_u32 s7, s97, 0
	global_load_dwordx4 v[48:51], v40, s[10:11]
	global_load_dwordx4 v[52:55], v40, s[10:11] offset:1024
	global_load_dwordx4 v[56:59], v40, s[10:11] offset:2048
	global_load_dwordx4 v[60:63], v40, s[10:11] offset:3072
	global_load_dword v80, v41, s[6:7]
	s_waitcnt vmcnt(9)
	s_branch .Lfin_go_b
